# conv unit, taps-already-staged path: removed the four s_waitcnt vmcnt(3..0) in front of the row loads (they only guarded tap-load destinations that this path never loads); row loads now issue without
# baseline (speedup 1.0000x reference)
; #define GAS __attribute__((address_space(1)))
; #define LAS __attribute__((address_space(3)))
; __device__ __forceinline__ void conv_unit(int cu, const bf16* U, const unsigned char* cw16, const float* cb, const float* lg, const float* lb, bf16* MIX, LAS unsigned char* lds, int tid, int wave, int lane, bool& w_staged, unsigned& nx, gu32* qctr) {
;     ...
;     v4u wv[4] = {}; v4u uv[8];
;     if (!w_staged) {
; #pragma unroll
;         for (int k = 0; k < 4; ++k) { const int i = tid + 512 * k; wv[k] = *(const GAS v4u*)(cw16 + (size_t)(i < KC * 64 ? i : 0) * 16); } }
; #pragma unroll
;     for (int k = 0; k < 8; ++k) { const int i = tid + 512 * k, rr = i >> 6, pc = i & 63, r = r0 - 15 + rr, rc = r < 0 ? 0 : (r > M - 1 ? M - 1 : r);
;         uv[k] = *(const GAS v4u*)(U + (size_t)rc * CW + pc * 8); }
;     if (!w_staged) {
; #pragma unroll
;         for (int k = 0; k < 4; ++k) { const int i = tid + 512 * k; if (i < KC * 64) *(LAS v4u*)(lds + CONV_W_LDS + i * 16) = wv[k]; }
;         w_staged = true; }
.LBB0_465:
	s_andn2_b64 vcc, exec, s[14:15]
	s_cbranch_vccnz .LBB0_467
	v_mov_b32_e32 v38, 0
	v_mov_b32_e32 v78, v44
	v_mov_b32_e32 v79, v43
	v_mov_b32_e32 v80, v42
	v_mov_b32_e32 v39, 0
	v_mov_b32_e32 v40, 0
	v_mov_b32_e32 v41, 0
	v_mov_b32_e32 v30, 0
	v_mov_b32_e32 v31, 0
	v_mov_b32_e32 v32, 0
	v_mov_b32_e32 v33, 0
	v_mov_b32_e32 v34, 0
	v_mov_b32_e32 v35, 0
	v_mov_b32_e32 v36, 0
	v_mov_b32_e32 v37, 0
	v_mov_b32_e32 v26, 0
	v_mov_b32_e32 v27, 0
	v_mov_b32_e32 v28, 0
	v_mov_b32_e32 v29, 0
